# dealt-unit loops: the next-ticket atomic returns straight into its holder register and its vmcnt(0) wait is dropped (first consumer is the end-of-unit publish) - attention, ssm2, conv, gmlp, cvt, xatt
# baseline (speedup 1.0000x reference)
; DI float fast_exp2(float x) { return __builtin_amdgcn_exp2f(x); }
; DI void lds_barrier() { asm volatile("s_waitcnt lgkmcnt(0)" ::: "memory"); __builtin_amdgcn_s_barrier(); asm volatile("" ::: "memory"); }
; template <int VAR>
; DI void attn_segment(const Args& a, const Frame& F, int l, int qrow0, int qpos0, int hp, int ntile, int nf32, const float* ck, const float* cv, int prow0) {
;     ...
;     const int fr = lane & 15, fq = lane >> 4;
;     const int hh = wave >> 2, h = 2 * hp + hh, qr = (wave & 3) * 16;
;     const float slope2 = exp2f(-2.f * (float)(h + 1)) * LOG2E;
;     const bf16* qp = P + (size_t)(qrow0 + qr + fr) * INW + 256 + h * 64 + 8 * fq;
;     const bf16x8 q1 = ld8g(qp), q2 = ld8g(qp + 32);
;     const int qpos_l = qr + fr;
;     const float adv = 64.f * slope2, decay = fast_exp2(-adv);
;     AtState S; S.ref = -1e30f; S.l1 = 0.f; S.l2 = 0.f;
; #pragma unroll
;     for (int dt = 0; dt < 4; ++dt) { S.O1[dt] = (f32x4){0.f, 0.f, 0.f, 0.f}; S.O2[dt] = (f32x4){0.f, 0.f, 0.f, 0.f};
; #pragma unroll
;         for (int j = 0; j < 4; ++j) S.cinit[dt][j] = 0.f; }
;     if (nf32 == 0) {
;         const char* pb = (const char*)(P + (size_t)prow0 * INW + 512 + hp * 128);
;         const unsigned voff = (unsigned)((tid >> 4) * INW + (tid & 15) * 8) * 2u; constexpr size_t TSTR = (size_t)64 * INW * 2;
;         AtRawB ra, rb;
;         atb_issue(ra, pb, voff); atb_commit(ra, F.lds, tid);
;         const int nl = ntile - 1;
;         atb_issue(ra, pb + (size_t)(nl < 1 ? nl : 1) * TSTR, voff);
;         lds_barrier();
.LBB0_1369:
	v_mov_b32_e32 v161, 0
	s_and_saveexec_b64 s[0:1], s[36:37]
	s_cbranch_execz .LBB0_1373
	s_mov_b64 s[14:15], exec
	v_mbcnt_lo_u32_b32 v3, s14, 0
	v_mbcnt_hi_u32_b32 v3, s15, v3
	v_cmp_eq_u32_e32 vcc, 0, v3
	s_and_saveexec_b64 s[2:3], vcc
	s_cbranch_execz .LBB0_1372
	s_bcnt1_i32_b64 s14, s[14:15]
	v_mov_b32_e32 v4, s14
	global_atomic_add v161, v2, v4, s[6:7] sc0
.LBB0_1372:
	s_or_b64 exec, exec, s[2:3]
.LBB0_1373:
	s_or_b64 exec, exec, s[0:1]
	s_add_i32 s21, s20, 0xffffff90
	s_cmp_gt_u32 s21, 63
	s_cbranch_scc0 .LBB0_1396
	s_sub_i32 s0, s20, 64
	s_cmpk_lt_i32 s20, 0x70
	s_cselect_b32 s0, s20, s0
	s_ashr_i32 s22, s0, 3
	s_and_b32 s14, s0, 1
	s_lshl_b32 s0, s0, 11
	s_and_b32 s15, s0, 0x3000
	s_lshl_b32 s0, s22, 6
	s_sub_i32 s23, 0xfc0, s0
	v_mov_b32_e32 v3, v0
	v_mov_b32_e32 v44, v160
	s_mov_b32 s0, s78
	s_ashr_i32 s17, s0, 2
	s_lshl_b32 s1, s14, 1
	s_add_i32 s2, s17, s1
	s_add_i32 s1, s2, 1
	v_cvt_f32_i32_e32 v45, s1
	s_lshl_b32 s0, s0, 4
	s_and_b32 s18, s0, 48
	s_mov_b32 s0, 0xc2fc0000
	v_mul_f32_e32 v4, -2.0, v45
	s_add_i32 s16, s23, s15
	s_sub_i32 s24, 64, s22
	v_cmp_gt_f32_e32 vcc, s0, v4
	s_and_b64 s[0:1], vcc, exec
	s_cselect_b32 s19, 0xffffffc0, 0
	s_lshl_b32 s2, s2, 6
	s_ashr_i32 s3, s2, 31
	s_lshl_b32 s0, s15, 12
	v_readlane_b32 s26, v253, 62
	v_readlane_b32 s27, v253, 63
	s_add_u32 s0, s26, s0
	s_addc_u32 s1, s27, 0
	s_lshl_b32 s14, s14, 8
	v_lshlrev_b32_e32 v5, 4, v3
	s_add_u32 s0, s0, s14
	v_lshlrev_b32_e32 v4, 8, v3
	v_and_b32_e32 v47, 0xf0, v5
	s_movk_i32 s14, 0xf000
	v_and_b32_e32 v48, 15, v44
	v_and_or_b32 v144, v4, s14, v47
	v_or_b32_e32 v4, s16, v48
	s_addc_u32 s1, s1, 0
	v_add_u32_e32 v146, 0x20000, v144
	v_or_b32_e32 v140, s18, v4
	global_load_dwordx4 v[28:31], v144, s[0:1] offset:1024
	global_load_dwordx4 v[32:35], v144, s[0:1] offset:1536
	global_load_dwordx4 v[36:39], v146, s[0:1] offset:1024
	global_load_dwordx4 v[40:43], v146, s[0:1] offset:1536
	v_ashrrev_i32_e32 v141, 31, v140
	s_sub_i32 s25, 63, s22
	v_ashrrev_i32_e32 v49, 4, v44
	v_lshlrev_b64 v[4:5], 12, v[140:141]
	s_cmp_eq_u32 s22, 63
	v_lshl_add_u64 v[4:5], s[26:27], 0, v[4:5]
	v_lshlrev_b32_e32 v6, 3, v49
	s_cselect_b32 s14, 0, 0x40000
	v_lshl_add_u64 v[4:5], s[2:3], 1, v[4:5]
	v_ashrrev_i32_e32 v7, 31, v6
	s_add_u32 s14, s0, s14
	v_lshl_add_u64 v[8:9], v[6:7], 1, v[4:5]
	s_addc_u32 s15, s1, 0
	global_load_dwordx4 v[4:7], v[8:9], off offset:512
	s_nop 0
	global_load_dwordx4 v[8:11], v[8:9], off offset:576
	s_nop 0
	global_load_dwordx4 v[12:15], v144, s[14:15] offset:1024
	global_load_dwordx4 v[16:19], v144, s[14:15] offset:1536
	global_load_dwordx4 v[20:23], v146, s[14:15] offset:1024
	global_load_dwordx4 v[24:27], v146, s[14:15] offset:1536
	v_cndmask_b32_e32 v46, 0, v201, vcc
	v_fmac_f32_e32 v46, -2.0, v45
	v_exp_f32_e32 v45, v46
	v_ashrrev_i32_e32 v50, 4, v3
	v_add_u32_e32 v3, 0x200, v3
	s_movk_i32 s14, 0x110
	s_movk_i32 s15, 0x120
	v_ashrrev_i32_e32 v3, 4, v3
	v_mul_lo_u32 v53, v50, s14
	v_lshlrev_b32_e32 v142, 2, v49
	v_add_u32_e32 v47, 0, v47
	v_mul_lo_u32 v49, v3, s14
	v_mul_lo_u32 v3, v3, s15
	v_mul_lo_u32 v50, v50, s15
	v_add_u32_e32 v143, v47, v53
	v_add_u32_e32 v204, v47, v3
	v_ldexp_f32 v3, v45, s19
	v_add_u32_e32 v202, v47, v50
	v_add_u32_e32 v203, v47, v49
	v_mul_f32_e32 v148, 0x3fb8aa3b, v3
	v_mul_f32_e32 v205, 0x42800000, v148
	v_bfe_u32 v51, v44, 2, 2
	v_exp_f32_e64 v150, -v205
	s_lshl_b32 s14, s17, 7
	v_and_b32_e32 v52, -16, v44
	v_or_b32_e32 v51, v142, v51
	v_lshlrev_b32_e32 v3, 3, v44
	s_add_i32 s14, s14, 0
	v_mul_u32_u24_e32 v56, 0x110, v48
	v_or_b32_e32 v48, s18, v48
	v_and_b32_e32 v3, 24, v3
	v_mov_b32_e32 v53, v2
	v_mov_b32_e32 v54, v2
	v_mov_b32_e32 v55, v2
	v_sub_u32_e32 v206, v48, v142
	s_mov_b32 s26, 3
	v_mov_b32_e32 v145, v2
	v_mov_b32_e32 v147, v2
	v_mov_b32_e32 v152, v150
	s_waitcnt vmcnt(0)
	ds_write_b128 v143, v[28:31]
	ds_write_b128 v202, v[32:35] offset:17408
	ds_write_b128 v203, v[36:39]
	ds_write_b128 v204, v[40:43] offset:17408
	v_cvt_f32_i32_e32 v29, s23
	s_waitcnt lgkmcnt(0)
	s_barrier
	v_mul_lo_u32 v28, v51, s15
	v_mul_f32_e64 v207, v29, -v148
	v_add_u32_e32 v29, s14, v52
	v_mov_b32_e32 v52, v2
	v_add3_u32 v208, s14, v3, v28
	v_mov_b32_e32 v3, v2
	v_add_u32_e32 v213, v29, v56
	v_mov_b64_e32 v[48:49], v[52:53]
	v_mov_b64_e32 v[44:45], v[52:53]
	v_mov_b64_e32 v[94:95], v[54:55]
	v_mov_b64_e32 v[102:103], v[54:55]
	v_mov_b64_e32 v[70:71], v[54:55]
	v_mov_b64_e32 v[74:75], v[54:55]
	v_mov_b64_e32 v[86:87], v[54:55]
	v_mov_b64_e32 v[90:91], v[54:55]
	v_mov_b64_e32 v[62:63], v[54:55]
	v_mov_b64_e32 v[66:67], v[54:55]
	v_mov_b64_e32 v[58:59], v[54:55]
	v_mov_b32_e32 v153, v150
	v_add_u32_e32 v209, 0xf400, v208
	v_add_u32_e32 v210, 0xf420, v208
	v_add_u32_e32 v211, 0xf440, v208
	v_add_u32_e32 v212, 0xf460, v208
	v_mov_b32_e32 v154, v150
	v_mov_b32_e32 v155, v150
	v_mov_b32_e32 v149, v148
	v_mov_b32_e32 v214, 0xf149f2ca
	v_mov_b64_e32 v[50:51], v[54:55]
	v_mov_b64_e32 v[46:47], v[54:55]
	v_mov_b64_e32 v[92:93], v[52:53]
	v_mov_b64_e32 v[100:101], v[52:53]
	v_mov_b64_e32 v[68:69], v[52:53]
	v_mov_b64_e32 v[72:73], v[52:53]
	v_mov_b64_e32 v[84:85], v[52:53]
	v_mov_b64_e32 v[88:89], v[52:53]
	v_mov_b64_e32 v[60:61], v[52:53]
	v_mov_b64_e32 v[64:65], v[52:53]
	v_mov_b64_e32 v[56:57], v[52:53]
	v_mov_b64_e32 v[156:157], v[2:3]
	s_branch .LBB0_1376

; #define LAS __attribute__((address_space(3)))
; DI void ssm_pass2_unit(const Args& a, const Frame& F, int l, int unit) {
;     const unsigned char* sm = a.ws + WS_W + (size_t)l * LW + W_SMALL;
;     const bf16* P = (const bf16*)(a.ws + WS_P); const float* E = (const float*)(a.ws + WS_SSME); bf16* MIX = (bf16*)(a.ws + WS_MIX);
;     int lane = F.lane; asm volatile("" : "+v"(lane));
;     const int fr = lane & 15, fq = lane >> 4;
;     const bool prompt = unit < 256; const int b = prompt ? (unit >> 6) : (unit - 256), ck = prompt ? (unit & 63) : 0;
;     const int row0 = prompt ? b * TP + ck * 64 : NP + b * 64;
;     LAS unsigned char* wl = F.lds + F.wave * SSM_WREG; LAS bf16* G = (LAS bf16*)(F.lds + SSM_G);
.LBB0_1437:
	v_mov_b32_e32 v164, 0
	s_and_saveexec_b64 s[0:1], s[24:25]
	s_cbranch_execz .LBB0_1441
	s_mov_b64 s[4:5], exec
	v_mbcnt_lo_u32_b32 v4, s4, 0
	v_mbcnt_hi_u32_b32 v4, s5, v4
	v_cmp_eq_u32_e32 vcc, 0, v4
	s_and_saveexec_b64 s[2:3], vcc
	s_cbranch_execz .LBB0_1440
	s_bcnt1_i32_b64 s4, s[4:5]
	v_mov_b32_e32 v5, s4
	v_readlane_b32 s4, v249, 33
	v_readlane_b32 s5, v249, 34
	s_nop 4
	global_atomic_add v164, v2, v5, s[4:5] offset:768 sc0
.LBB0_1440:
	s_or_b64 exec, exec, s[2:3]
.LBB0_1441:
	s_or_b64 exec, exec, s[0:1]
	s_cmpk_gt_i32 s7, 0xff
	s_cselect_b64 s[24:25], -1, 0
	s_cmpk_lt_i32 s7, 0x100
	s_cselect_b64 s[0:1], -1, 0
	v_writelane_b32 v249, s0, 62
	s_min_i32 s3, s7, 0x100
	v_mov_b32_e32 v74, v160
	v_writelane_b32 v249, s1, 63
	s_ashr_i32 s70, s7, 6
	s_and_b32 s6, s3, 63
	s_mov_b64 s[0:1], -1
	s_and_b64 vcc, exec, s[24:25]
	s_cbranch_vccnz .LBB0_1443
	s_lshl_b32 s0, s70, 12
	s_lshl_b32 s1, s6, 6
	s_or_b32 s2, s1, s0
	s_mov_b64 s[0:1], 0

; #define LAS __attribute__((address_space(3)))
; DI void conv_unit(const Args& a, const Frame& F, int l, int unit) {
;     const unsigned char* sm = a.ws + WS_W + (size_t)l * LW + W_SMALL;
;     const bf16* P = (const bf16*)(a.ws + WS_P); bf16* MIX = (bf16*)(a.ws + WS_MIX);
;     int lane = F.lane, tid = F.tid;
;     asm volatile("" : "+v"(lane), "+v"(tid));
;     const bool prompt = unit < 256; const int b = prompt ? (unit >> 6) : (unit - 256), tt = prompt ? (unit & 63) : 0;
;     const int row0 = prompt ? b * TP + tt * 64 : NP + b * 64;
;     LAS bf16* Z = (LAS bf16*)(F.lds + CV_Z); LAS float* Y = (LAS float*)(F.lds + CV_Y);
;     const bool wbuf = !prompt || tt == 63;
;     float* obuf = prompt ? a.out + O_PCV + (size_t)(l * BP + b) * 30 * 256 : a.out + O_SCV + (size_t)(l * BS + b) * 30 * 256;
.LBB0_1495:
	v_mov_b32_e32 v3, 0
	s_and_saveexec_b64 s[0:1], s[36:37]
	s_cbranch_execz .LBB0_1499
	s_mov_b64 s[4:5], exec
	v_mbcnt_lo_u32_b32 v3, s4, 0
	v_mbcnt_hi_u32_b32 v3, s5, v3
	v_cmp_eq_u32_e32 vcc, 0, v3
	s_and_saveexec_b64 s[2:3], vcc
	s_cbranch_execz .LBB0_1498
	s_bcnt1_i32_b64 s4, s[4:5]
	v_mov_b32_e32 v4, s4
	v_readlane_b32 s4, v249, 33
	v_readlane_b32 s5, v249, 34
	s_nop 4
	global_atomic_add v3, v2, v4, s[4:5] sc0
.LBB0_1498:
	s_or_b64 exec, exec, s[2:3]
.LBB0_1499:
	s_or_b64 exec, exec, s[0:1]
	s_cmpk_gt_i32 s16, 0xff
	s_cselect_b64 s[0:1], -1, 0
	s_min_i32 s2, s16, 0x100
	v_mov_b32_e32 v111, v0
	v_mov_b32_e32 v108, v160
	s_and_b32 s26, s2, 63
	s_mov_b64 s[4:5], -1
	s_and_b64 vcc, exec, s[0:1]
	s_cbranch_vccnz .LBB0_1501
	s_ashr_i32 s27, s16, 6
	s_lshl_b32 s2, s27, 12
	s_lshl_b32 s3, s26, 6
	s_or_b32 s24, s3, s2
	s_mov_b64 s[4:5], 0

; #define LAS __attribute__((address_space(3)))
; template <int L>
; DI void gmlp_unit_t(const Args& a, const Frame& F, int l, int row0, float* gv_out) {
;     const unsigned char* sm = a.ws + WS_W + (size_t)l * LW + W_SMALL;
;     const bf16* P = (const bf16*)(a.ws + WS_P); bf16* MIX = (bf16*)(a.ws + WS_MIX);
;     const int lane = F.lane, fr = lane & 15, fq = lane >> 4;
;     LAS unsigned char* VL = F.lds;
;     const int h = F.wave >> 1; const bf16* Wm = (const bf16*)(sm + S_GMLPW) + (size_t)h * 128 * 128;
;     bf16x8 af[L / 32][L / 32]; float bsv[L / 32][4];
; #pragma unroll
;     for (int r = 0; r < L / 32; ++r) { const int it = (F.wave & 1) * (L / 32) + r;
; #pragma unroll
;         for (int ks = 0; ks < L / 32; ++ks) { const bf16* wr_ = Wm + (size_t)(16 * it + fr) * 128 + 32 * ks + 4 * fq; af[r][ks] = cat44(*(const u32x2*)wr_, *(const u32x2*)(wr_ + 16)); }
; #pragma unroll
;         for (int j = 0; j < 4; ++j) bsv[r][j] = a.in[I_GBS][(l * 4 + h) * 128 + 16 * it + 4 * fq + j]; }
;     {
;         const f32x4 lg = ((const f32x4*)(a.in[I_GLG] + l * 256))[lane], lb = ((const f32x4*)(a.in[I_GLB] + l * 256))[lane];
;         for (int t0 = F.wave; t0 < L; t0 += 4 * NWAVES) {
;             u32x2 raw[4];
; #pragma unroll
;             for (int r = 0; r < 4; ++r) raw[r] = *(const u32x2*)(P + (size_t)(row0 + t0 + r * NWAVES) * INW + 1792 + 4 * lane);
;             f32x4 v[4]; float st[8];
; #pragma unroll
;             for (int r = 0; r < 4; ++r) { v[r] = (f32x4){bflo(raw[r].x), bfhi(raw[r].x), bflo(raw[r].y), bfhi(raw[r].y)};
;                 st[r] = (v[r][0] + v[r][1]) + (v[r][2] + v[r][3]); st[4 + r] = (v[r][0] * v[r][0] + v[r][1] * v[r][1]) + (v[r][2] * v[r][2] + v[r][3] * v[r][3]); }
;             wave_sum_n<8>(st);
.LBB0_1532:
	v_mov_b32_e32 v151, 0
	s_and_saveexec_b64 s[0:1], s[36:37]
	s_cbranch_execz .LBB0_1536
	s_mov_b64 s[20:21], exec
	v_mbcnt_lo_u32_b32 v4, s20, 0
	v_mbcnt_hi_u32_b32 v4, s21, v4
	v_cmp_eq_u32_e32 vcc, 0, v4
	s_and_saveexec_b64 s[2:3], vcc
	s_cbranch_execz .LBB0_1535
	s_bcnt1_i32_b64 s20, s[20:21]
	v_mov_b32_e32 v5, s20
	v_readlane_b32 s20, v249, 33
	v_readlane_b32 s21, v249, 34
	s_nop 4
	global_atomic_add v151, v2, v5, s[20:21] offset:256 sc0
.LBB0_1535:
	s_or_b64 exec, exec, s[2:3]
.LBB0_1536:
	s_or_b64 exec, exec, s[0:1]
	s_cmpk_gt_i32 s33, 0x7f
	s_mov_b64 s[0:1], -1
	s_cbranch_scc0 .LBB0_1545
	global_load_dwordx2 v[24:25], v[88:89], off
	global_load_dwordx2 v[26:27], v[88:89], off offset:32
	global_load_dwordx2 v[20:21], v[88:89], off offset:64
	global_load_dwordx2 v[22:23], v[88:89], off offset:96
	global_load_dwordx4 v[16:19], v[90:91], off
	global_load_dwordx2 v[12:13], v[92:93], off
	global_load_dwordx2 v[14:15], v[92:93], off offset:32
	global_load_dwordx2 v[8:9], v[92:93], off offset:64
	global_load_dwordx2 v[10:11], v[92:93], off offset:96
	global_load_dwordx4 v[4:7], v[94:95], off
	s_andn2_b64 vcc, exec, s[4:5]
	s_cbranch_vccnz .LBB0_1540
	global_load_dwordx4 v[28:31], v[96:97], off
	global_load_dwordx4 v[32:35], v[98:99], off
	v_and_b32_e32 v36, 64, v198
	v_add_u32_e32 v36, 64, v36
	v_xor_b32_e32 v37, 1, v198
	v_cmp_lt_i32_e32 vcc, v37, v36
	v_readlane_b32 s0, v252, 53
	s_add_i32 s0, s0, s33
	v_cndmask_b32_e32 v37, v198, v37, vcc
	v_lshlrev_b32_e32 v64, 2, v37
	v_xor_b32_e32 v37, 2, v198
	v_cmp_lt_i32_e32 vcc, v37, v36
	s_ashr_i32 s1, s0, 31
	s_lshl_b64 s[2:3], s[0:1], 16
	v_cndmask_b32_e32 v37, v198, v37, vcc
	v_lshlrev_b32_e32 v65, 2, v37
	v_xor_b32_e32 v37, 4, v198
	v_cmp_lt_i32_e32 vcc, v37, v36
	s_add_u32 s0, s15, s2
	s_addc_u32 s1, s27, s3
	v_cndmask_b32_e32 v37, v198, v37, vcc
	v_lshlrev_b32_e32 v66, 2, v37
	v_xor_b32_e32 v37, 8, v198
	v_cmp_lt_i32_e32 vcc, v37, v36
	s_add_u32 s20, s17, s2
	s_addc_u32 s21, s28, s3
	v_cndmask_b32_e32 v37, v198, v37, vcc
	v_lshlrev_b32_e32 v67, 2, v37
	v_xor_b32_e32 v37, 16, v198
	v_cmp_lt_i32_e32 vcc, v37, v36
	s_add_u32 s22, s19, s2
	s_addc_u32 s23, s29, s3
	v_cndmask_b32_e32 v37, v198, v37, vcc
	v_lshlrev_b32_e32 v68, 2, v37
	v_xor_b32_e32 v37, 32, v198
	v_cmp_lt_i32_e32 vcc, v37, v36
	s_add_u32 s24, s34, s2
	s_addc_u32 s25, s35, s3
	v_cndmask_b32_e32 v36, v198, v37, vcc
	v_lshlrev_b32_e32 v69, 2, v36
	s_lshl_b32 s38, s33, 6
	v_mov_b32_e32 v70, v131
	s_mov_b32 s39, s26

; #define LAS __attribute__((address_space(3)))
; DI BigDesc big_desc(const Args& a, int it, int& n0) {
;     const int l = it / BT_LAYER; int r = it % BT_LAYER;
;     unsigned char* ws = a.ws; unsigned char* wl = ws + WS_W + (size_t)l * LW;
;     const size_t oFF = (size_t)l * DM * DFF, oIN = (size_t)l * DM * INW, oDD = (size_t)l * DM * DM, oXQ = (size_t)l * DM * XW;
;     if (r < BT_FF) return big_mk(a.in[I_F1G] + oFF, DM, DFF, a.in[I_F1N] + l * DM, (bf16*)(wl + W_GU1), 0, 1, r, 0, n0); r -= BT_FF;
;     if (r < BT_FF) return big_mk(a.in[I_F1U] + oFF, DM, DFF, a.in[I_F1N] + l * DM, (bf16*)(wl + W_GU1), 0, 2, r, 0, n0); r -= BT_FF;
;     if (r < BT_DN) return big_mk(a.in[I_F1D] + oFF, DFF, DM, nullptr, (bf16*)(wl + W_D1), 0, 0, r, ALD, n0); r -= BT_DN;
;     if (r < BT_IN) return big_mk(a.in[I_WIN] + oIN, DM, INW, a.in[I_MIXN] + l * DM, (bf16*)(wl + W_IN), 0, 0, r, 0, n0); r -= BT_IN;
;     if (r < BT_Q) return big_mk(a.in[I_XWK] + oXQ, DM, XW, a.in[I_MEMNORM] + l * DM, (bf16*)(ws + WS_WKV), l * 1024, 0, r, 0, n0); r -= BT_Q;
;     if (r < BT_Q) return big_mk(a.in[I_XWV] + oXQ, DM, XW, a.in[I_MEMNORM] + l * DM, (bf16*)(ws + WS_WKV), l * 1024 + 512, 0, r, 0, n0); r -= BT_Q;
;     if (r < BT_FF) return big_mk(a.in[I_F2G] + oFF, DM, DFF, a.in[I_F2N] + l * DM, (bf16*)(wl + W_GU2), 0, 1, r, 0, n0); r -= BT_FF;
;     if (r < BT_FF) return big_mk(a.in[I_F2U] + oFF, DM, DFF, a.in[I_F2N] + l * DM, (bf16*)(wl + W_GU2), 0, 2, r, 0, n0); r -= BT_FF;
;     if (r < BT_DN) return big_mk(a.in[I_F2D] + oFF, DFF, DM, nullptr, (bf16*)(wl + W_D2), 0, 0, r, ALD, n0); r -= BT_DN;
;     if (r < BT_OUT) return big_mk(a.in[I_WOUT] + oDD, DM, DM, nullptr, (bf16*)(wl + W_OUT), 0, 0, r, 0, n0); r -= BT_OUT;
;     if (r < BT_Q) return big_mk(a.in[I_XWQ] + oXQ, DM, XW, a.in[I_XN] + l * DM, (bf16*)(wl + W_Q), 0, 0, r, 0, n0); r -= BT_Q;
;     return big_mk(a.in[I_XWO] + oXQ, XW, DM, nullptr, (bf16*)(wl + W_O), 0, 0, r, 0, n0);
; }
; DI void cvt_unit(const Args& a, const Frame& F, int it0) {
;     LAS float* T = (LAS float*)F.lds;
;     int n0 = 0, n1 = 0; f32x4 w[16];
;     BigDesc d = big_desc(a, it0, n0); big_load(d, F.tid, w);
.LBB0_1575:
	v_mov_b32_e32 v136, 0
	s_and_saveexec_b64 s[0:1], s[8:9]
	s_cbranch_execz .LBB0_1579
	s_mov_b64 s[4:5], exec
	v_mbcnt_lo_u32_b32 v4, s4, 0
	v_mbcnt_hi_u32_b32 v4, s5, v4
	v_cmp_eq_u32_e32 vcc, 0, v4
	s_and_saveexec_b64 s[2:3], vcc
	s_cbranch_execz .LBB0_1578
	s_bcnt1_i32_b64 s4, s[4:5]
	v_mov_b32_e32 v5, s4
	v_readlane_b32 s4, v249, 33
	v_readlane_b32 s5, v249, 34
	s_nop 4
	global_atomic_add v136, v2, v5, s[4:5] offset:2816 sc0
.LBB0_1578:
	s_or_b64 exec, exec, s[2:3]
.LBB0_1579:
	s_or_b64 exec, exec, s[0:1]
	s_lshl_b32 s0, s6, 1
	v_readlane_b32 s1, v248, 0
	s_add_i32 s18, s1, s0
	s_mul_hi_i32 s0, s18, 0x8d3dcb09
	s_add_i32 s0, s0, s18
	s_lshr_b32 s1, s0, 31
	s_ashr_i32 s0, s0, 9
	s_add_i32 s2, s0, s1
	s_mul_i32 s0, s2, 0x3a0
	s_sub_i32 s21, s18, s0
	s_ashr_i32 s3, s2, 31
	s_mul_i32 s1, s2, 0x3b00000
	v_readlane_b32 s4, v252, 7
	s_mul_hi_i32 s0, s2, 0x3b00000
	s_add_u32 s19, s4, s1
	v_readlane_b32 s1, v252, 8
	s_addc_u32 s20, s1, s0
	s_lshl_b64 s[8:9], s[2:3], 22
	s_cmpk_gt_i32 s21, 0x7f
	s_mov_b64 s[14:15], -1
	s_cbranch_scc0 .LBB0_1620
	s_cmpk_gt_u32 s21, 0xff
	s_cbranch_scc0 .LBB0_1617
	s_cmpk_gt_u32 s21, 0x17f
	s_cbranch_scc0 .LBB0_1614
	s_cmpk_gt_u32 s21, 0x1bf
	s_cbranch_scc0 .LBB0_1611
	s_lshl_b64 s[14:15], s[2:3], 19
	s_cmpk_gt_u32 s21, 0x1cf
	s_mov_b64 s[16:17], -1
	s_cbranch_scc0 .LBB0_1608
	s_cmpk_gt_u32 s21, 0x1df
	s_cbranch_scc0 .LBB0_1605
	s_cmpk_gt_u32 s21, 0x25f
	s_cbranch_scc0 .LBB0_1602
	s_cmpk_gt_u32 s21, 0x2df
	s_mov_b64 s[6:7], -1
	s_cbranch_scc0 .LBB0_1599
	s_cmpk_gt_u32 s21, 0x35f
	s_cbranch_scc0 .LBB0_1596
	s_cmpk_gt_u32 s21, 0x37f
	s_cbranch_scc0 .LBB0_1593
	s_cmpk_gt_u32 s21, 0x38f
	s_mov_b64 s[4:5], -1
	s_cbranch_scc0 .LBB0_1591
	v_readlane_b32 s36, v251, 28
	s_lshl_b64 s[0:1], s[14:15], 2
	v_readlane_b32 s48, v251, 40
	v_readlane_b32 s49, v251, 41
	s_add_u32 s0, s48, s0
	s_addc_u32 s1, s49, s1
	s_lshl_b32 s4, s21, 5
	s_addk_i32 s4, 0xe00
	s_and_b32 s4, s4, 0x1fc0
	s_lshl_b32 s5, s4, 12
	s_add_u32 s10, s0, s5
	s_addc_u32 s11, s1, 0
	s_lshl_b32 s0, s4, 1
	s_add_u32 s0, s19, s0
	s_addc_u32 s1, s20, 0
	s_add_u32 s0, s0, 0x2000000
	v_readlane_b32 s37, v251, 29
	v_readlane_b32 s38, v251, 30
	v_readlane_b32 s39, v251, 31
	v_readlane_b32 s40, v251, 32
	v_readlane_b32 s41, v251, 33
	v_readlane_b32 s42, v251, 34
	v_readlane_b32 s43, v251, 35
	v_readlane_b32 s44, v251, 36
	v_readlane_b32 s45, v251, 37
	v_readlane_b32 s46, v251, 38
	v_readlane_b32 s47, v251, 39
	v_readlane_b32 s50, v251, 42
	v_readlane_b32 s51, v251, 43
	s_addc_u32 s1, s1, 0
	s_mov_b64 s[4:5], 0

; DI void xattn_unit(const Args& a, const Frame& F, int l, int unit) {
;     const bf16* Q = (const bf16*)(a.ws + WS_Q); bf16* OX = (bf16*)(a.ws + WS_OX);
;     int lane = F.lane, tid = F.tid; asm volatile("" : "+v"(lane), "+v"(tid));
;     const int fr = lane & 15, fq = lane >> 4;
;     const bool prompt = unit < 128;
;     int b, h, row0, nrg;
;     if (prompt) { b = unit >> 5; h = (unit >> 3) & 3; row0 = b * TP + (unit & 7) * 512; nrg = 32; }
;     else { const int u = unit - 128; b = u >> 2; h = u & 3; row0 = NP + b * 64; nrg = 4; }
.LBB0_2026:
	v_mov_b32_e32 v3, 0
	s_and_saveexec_b64 s[0:1], s[36:37]
	s_cbranch_execz .LBB0_2030
	s_mov_b64 s[8:9], exec
	v_mbcnt_lo_u32_b32 v3, s8, 0
	v_mbcnt_hi_u32_b32 v3, s9, v3
	v_cmp_eq_u32_e32 vcc, 0, v3
	s_and_saveexec_b64 s[6:7], vcc
	s_cbranch_execz .LBB0_2029
	s_bcnt1_i32_b64 s8, s[8:9]
	v_mov_b32_e32 v4, s8
	global_atomic_add v3, v2, v4, s[4:5] sc0
.LBB0_2029:
	s_or_b64 exec, exec, s[6:7]
.LBB0_2030:
	s_or_b64 exec, exec, s[0:1]
	s_cmpk_gt_i32 s14, 0x7f
	s_cselect_b64 s[0:1], -1, 0
	v_mov_b32_e32 v95, v160
	s_waitcnt vmcnt(0)
	v_mov_b32_e32 v8, v0
	s_mov_b64 s[6:7], -1
	s_and_b64 vcc, exec, s[0:1]
	s_cbranch_vccz .LBB0_2032
	s_add_i32 s6, s14, 0xffffff80
	s_lshr_b32 s13, s6, 2
	s_lshl_b32 s6, s13, 6
	s_add_i32 s9, s6, 0x4000
	s_mov_b64 s[6:7], 0
